# XCC-local barriers for the token-local chain (proj epilogue -> norm2 -> up -> down -> norm1): 15 of 29 seams wait only for the 32 workgroups of the same XCC, no L2 write-back; runtime guard falls back
# speedup vs baseline: 1.0540x; 1.0205x over previous
_Z10fwd_kernel6Params:
	s_load_dwordx4 s[68:71], s[0:1], 0xe0
	v_and_b32_e32 v1, 0x3ff, v0
	v_writelane_b32 v240, s2, 0
	s_add_u32 s2, s0, 0xf0
	v_readfirstlane_b32 s4, v1
	v_mbcnt_lo_u32_b32 v2, -1, 0
	v_writelane_b32 v240, s0, 1
	s_addc_u32 s3, s1, 0
	s_and_b32 s8, s4, 0xffffffc0
	v_mbcnt_hi_u32_b32 v2, -1, v2
	v_writelane_b32 v240, s1, 2
	v_add_u32_e32 v2, s8, v2
	v_writelane_b32 v240, s2, 3
	v_cmp_gt_i32_e32 vcc, 16, v2
	s_nop 0
	v_writelane_b32 v240, s3, 4
	s_and_saveexec_b64 s[0:1], vcc
	v_lshl_add_u32 v3, v2, 2, 0
	v_add_u32_e32 v3, 0x23fc0, v3
	v_mov_b32_e32 v4, 0
	ds_write_b32 v3, v4
	s_or_b64 exec, exec, s[0:1]
	v_readlane_b32 s0, v240, 1
	v_readlane_b32 s1, v240, 2
	s_load_dwordx2 s[60:61], s[0:1], 0xf0
	s_waitcnt lgkmcnt(0)
	s_add_u32 s0, s68, 0x80000
	s_addc_u32 s1, s69, 0
	s_barrier
	v_writelane_b32 v240, s0, 5
	v_cmp_eq_u32_e32 vcc, 0, v2
	s_getreg_b32 s5, hwreg(HW_REG_XCC_ID, 0, 4)
	v_writelane_b32 v240, s1, 6
	s_and_saveexec_b64 s[0:1], vcc
	s_cbranch_execz .LBB0_5
	s_mov_b64 s[2:3], exec
	v_mbcnt_lo_u32_b32 v2, s2, 0
	v_mbcnt_hi_u32_b32 v2, s3, v2
	v_cmp_eq_u32_e32 vcc, 0, v2
	s_and_b64 s[6:7], exec, vcc
	s_mov_b64 exec, s[6:7]
	s_cbranch_execz .LBB0_5
	s_lshl_b32 s5, s5, 8
	s_bcnt1_i32_b64 s2, s[2:3]
	s_and_b32 s5, s5, 0xf00
	v_mov_b32_e32 v3, s2
	v_readlane_b32 s2, v240, 5
	v_mov_b32_e32 v2, s5
	v_readlane_b32 s3, v240, 6
	v_readlane_b32 s6, v240, 0
	s_lshr_b32 s7, s5, 8
	s_lshl_b32 s7, 1, s7
	v_mov_b32_e32 v5, s7
	s_nop 2
	s_and_b32 s6, s6, 7
	s_lshl_b32 s6, s6, 8
	s_add_u32 s6, s6, 0x10000
	v_mov_b32_e32 v4, s6
	s_nop 1
	global_atomic_or v4, v5, s[2:3]
	s_waitcnt vmcnt(0)
	global_atomic_add v2, v3, s[2:3] offset:1024
.LBB0_5:
	s_or_b64 exec, exec, s[0:1]
	s_cmp_ge_i32 s70, s71
	s_cbranch_scc1 .LBB0_474
	v_readlane_b32 s2, v240, 0
	s_lshl_b32 s6, s60, 3
	s_lshl_b32 s7, s2, 3
	s_lshl_b32 s58, s60, 5
	s_cmpk_lt_u32 s2, 0xc0
	s_cselect_b64 s[0:1], -1, 0
	v_writelane_b32 v240, s0, 7
	s_lshl_b32 s64, s60, 9
	v_lshrrev_b32_e32 v3, 20, v0
	v_writelane_b32 v240, s1, 8
	s_add_i32 s0, s60, s2
	s_lshl_b32 s1, s2, 9
	s_cmpk_lt_i32 s2, 0x100
	v_writelane_b32 v240, s1, 9
	s_cselect_b64 s[2:3], -1, 0
	v_writelane_b32 v240, s2, 10
	s_cmp_gt_i32 s71, -1
	v_lshrrev_b32_e32 v0, 10, v0
	v_writelane_b32 v240, s3, 11
	s_cselect_b64 s[2:3], -1, 0
	v_writelane_b32 v240, s2, 12
	v_or_b32_e32 v0, v0, v3
	v_mov_b32_e32 v165, 0
	v_writelane_b32 v240, s3, 13
	s_add_u32 s2, s68, 0x80200
	s_addc_u32 s3, s69, 0
	s_add_u32 s72, s68, 0x80400
	v_writelane_b32 v240, s2, 14
	s_addc_u32 s73, s69, 0
	v_mov_b32_e32 v190, 0x358637bd
	v_writelane_b32 v240, s3, 15
	s_add_u32 s2, s68, 0x80500
	s_addc_u32 s3, s69, 0
	v_writelane_b32 v240, s2, 16
	v_mov_b32_e32 v191, 0x260
	s_mov_b32 s62, 0x12000
	v_writelane_b32 v240, s3, 17
	s_add_u32 s2, s68, 0x80600
	s_addc_u32 s3, s69, 0
	v_writelane_b32 v240, s2, 18
	v_mov_b32_e32 v192, 0x3fcc422a
	v_mov_b32_e32 v193, 0x3c0881c4
	v_writelane_b32 v240, s3, 19
	s_add_u32 s2, s68, 0x80700
	s_addc_u32 s3, s69, 0
	v_writelane_b32 v240, s2, 20
	v_mov_b32_e32 v194, 0xbab64f3b
	v_mov_b32_e32 v195, 0x3ab69700
	v_writelane_b32 v240, s3, 21
	s_add_u32 s2, s68, 0x80800
	s_addc_u32 s3, s69, 0
	v_writelane_b32 v240, s2, 22
	v_mov_b32_e32 v196, 0x1000
	v_mov_b32_e32 v197, 0x2000
	v_writelane_b32 v240, s3, 23
	s_add_u32 s2, s68, 0x80900
	s_addc_u32 s3, s69, 0
	v_writelane_b32 v240, s2, 24
	v_mov_b32_e32 v198, 1
	v_mov_b32_e32 v199, 0x100
	v_writelane_b32 v240, s3, 25
	s_add_u32 s2, s68, 0x80a00
	s_addc_u32 s3, s69, 0
	v_writelane_b32 v240, s2, 26
	v_mov_b32_e32 v200, 0x7fffea00
	v_mov_b32_e32 v201, 0x7ffff800
	v_writelane_b32 v240, s3, 27
	s_add_u32 s2, s68, 0x80b00
	s_addc_u32 s3, s69, 0
	v_writelane_b32 v240, s2, 28
	v_mov_b32_e32 v202, 13
	v_mov_b32_e32 v203, 2
	v_writelane_b32 v240, s3, 29
	s_add_u32 s2, s68, 0x80c00
	s_addc_u32 s3, s69, 0
	v_writelane_b32 v240, s2, 30
	v_mov_b32_e32 v204, 6
	v_mov_b32_e32 v205, 0x7f800000
	v_writelane_b32 v240, s3, 31
	s_add_u32 s2, s68, 0x80d00
	s_addc_u32 s3, s69, 0
	v_writelane_b32 v240, s2, 32
	v_not_b32_e32 v206, 63
	v_not_b32_e32 v207, 31
	v_writelane_b32 v240, s3, 33
	s_add_u32 s2, s68, 0x80e00
	s_addc_u32 s3, s69, 0
	v_writelane_b32 v240, s2, 34
	v_mov_b32_e32 v208, 0x7fc00000
	v_mov_b32_e32 v209, 0x7f000000
	v_writelane_b32 v240, s3, 35
	s_add_u32 s2, s68, 0x80f00
	s_addc_u32 s3, s69, 0
	v_writelane_b32 v240, s2, 36
	s_movk_i32 s74, 0x6000
	s_mov_b32 s75, 0x18000
	v_writelane_b32 v240, s3, 37
	s_add_u32 s2, s68, 0x81000
	s_addc_u32 s3, s69, 0
	v_writelane_b32 v240, s2, 38
	s_mov_b32 s94, 0x1e000
	s_mov_b32 s95, 0xc000
	v_writelane_b32 v240, s3, 39
	s_add_u32 s2, s68, 0x81100
	s_addc_u32 s3, s69, 0
	v_writelane_b32 v240, s2, 40
	s_mov_b32 s63, 0x42000
	s_mov_b32 s92, 0x24000
	v_writelane_b32 v240, s3, 41
	s_add_u32 s2, s68, 0x81200
	s_addc_u32 s3, s69, 0
	v_writelane_b32 v240, s2, 42
	s_mov_b32 s93, 0x3c000
	s_mov_b32 s96, 0x60000
	v_writelane_b32 v240, s3, 43
	s_add_u32 s2, s68, 0x81300
	s_addc_u32 s3, s69, 0
	v_writelane_b32 v240, s2, 44
	s_movk_i32 s97, 0x100
	s_nop 0
	v_writelane_b32 v240, s3, 45
	s_add_u32 s2, s68, 0x83400
	s_addc_u32 s3, s69, 0
	v_writelane_b32 v240, s2, 46
	s_nop 1
	v_writelane_b32 v240, s3, 47
	s_add_u32 s2, s68, 0x83500
	s_addc_u32 s3, s69, 0
	s_abs_i32 s1, s60
	v_cvt_f32_u32_e32 v2, s1
	v_writelane_b32 v240, s2, 48
	s_mul_i32 s69, s60, 24
	v_rcp_iflag_f32_e32 v2, v2
	v_writelane_b32 v240, s3, 49
	s_mul_i32 s2, s61, s60
	v_readlane_b32 s10, v240, 1
	v_readlane_b32 s11, v240, 2
	s_load_dword s3, s[10:11], 0xf8
	v_mul_f32_e32 v2, 0x4f7ffffe, v2
	v_cvt_u32_f32_e32 v2, v2
	s_waitcnt lgkmcnt(0)
	s_mul_i32 s2, s2, s3
	v_writelane_b32 v240, s2, 50
	s_movk_i32 s2, 0x3ff
	v_and_or_b32 v0, v0, s2, v1
	s_sub_i32 s2, 0, s1
	v_readfirstlane_b32 s3, v2
	v_cvt_f32_u32_e32 v1, s60
	s_mul_i32 s2, s2, s3
	s_mul_hi_u32 s2, s3, s2
	s_add_i32 s3, s3, s2
	s_mul_hi_u32 s2, s3, 0xc0
	v_rcp_iflag_f32_e32 v1, v1
	s_mul_i32 s2, s2, s1
	s_sub_i32 s2, 0xc0, s2
	s_sub_i32 s5, s2, s1
	s_cmp_ge_u32 s2, s1
	v_mul_f32_e32 v1, 0x4f7ffffe, v1
	s_cselect_b32 s2, s5, s2
	v_cvt_u32_f32_e32 v1, v1
	s_sub_i32 s5, s2, s1
	s_cmp_ge_u32 s2, s1
	s_cselect_b32 s2, s5, s2
	s_sub_i32 s0, s0, s2
	s_sub_i32 s2, 0, s60
	v_readfirstlane_b32 s5, v1
	s_mul_i32 s2, s2, s5
	s_mul_hi_u32 s2, s5, s2
	s_add_i32 s5, s5, s2
	s_mul_hi_u32 s2, s0, s5
	s_mul_i32 s2, s2, s60
	s_sub_i32 s0, s0, s2
	s_sub_i32 s2, s0, s60
	s_cmp_ge_u32 s0, s60
	s_cselect_b32 s0, s2, s0
	s_sub_i32 s2, s0, s60
	s_cmp_ge_u32 s0, s60
	s_cselect_b32 s0, s2, s0
	s_lshl_b32 s0, s0, 3
	v_writelane_b32 v240, s0, 51
	s_mul_hi_u32 s0, s3, 0x2c0
	s_mul_i32 s0, s0, s1
	s_sub_i32 s0, 0x2c0, s0
	s_sub_i32 s2, s0, s1
	s_cmp_ge_u32 s0, s1
	s_cselect_b32 s0, s2, s0
	s_sub_i32 s2, s0, s1
	s_cmp_ge_u32 s0, s1
	s_cselect_b32 s0, s2, s0
	v_writelane_b32 v240, s0, 52
	s_sub_i32 s0, s60, s0
	s_lshl_b32 s0, s0, 3
	v_writelane_b32 v240, s0, 53
	s_lshl_b32 s0, s4, 2
	s_and_b32 s0, s0, 0xffffff00
	s_add_i32 s0, s0, 0
	v_writelane_b32 v240, s0, 54
	v_writelane_b32 v240, s8, 55
	v_writelane_b32 v240, s6, 56
	s_add_i32 s0, s7, s6
	v_writelane_b32 v240, s0, 57
	s_add_i32 s0, s7, 0xfffff000
	v_writelane_b32 v240, s0, 58
	s_add_i32 s0, 0, 0x20000
	v_writelane_b32 v240, s0, 59
	s_add_i32 s0, 0, 0x23fc0
	v_writelane_b32 v240, s0, 60
	s_add_i32 s0, 0, 0x23fc4
	v_writelane_b32 v240, s0, 61
	s_mov_b32 s1, 0
	v_writelane_b32 v240, s0, 62
	s_ashr_i32 s65, s64, 31
	s_ashr_i32 s59, s58, 31
	v_writelane_b32 v240, s1, 63
	v_cmp_eq_u32_e64 s[0:1], 0, v0
	s_mov_b32 s4, s60
	s_lshl_b32 s68, s60, 4
	v_writelane_b32 v239, s0, 0
	s_lshl_b32 s25, s60, 10
	s_lshl_b32 s24, s60, 12
	v_writelane_b32 v239, s1, 1
	s_lshl_b64 s[0:1], s[64:65], 2
	v_writelane_b32 v239, s0, 2
	s_mov_b32 s2, 0x30000
	s_nop 0
	v_writelane_b32 v239, s1, 3
	s_lshl_b64 s[0:1], s[64:65], 6
	v_writelane_b32 v239, s0, 4
	s_nop 1
	v_writelane_b32 v239, s1, 5
	s_lshl_b64 s[0:1], s[58:59], 11
	v_writelane_b32 v239, s0, 6
	s_nop 1
	v_writelane_b32 v239, s1, 7
	s_lshl_b64 s[0:1], s[58:59], 12
	v_writelane_b32 v239, s0, 8
	s_nop 1
	v_writelane_b32 v239, s1, 9
	v_writelane_b32 v239, s4, 10
	s_mov_b64 s[0:1], 0x80
	s_nop 0
	v_writelane_b32 v239, s5, 11
	v_writelane_b32 v239, s7, 12
	v_writelane_b32 v239, s58, 13
	s_nop 1
	v_writelane_b32 v239, s59, 14
	v_writelane_b32 v239, s68, 15
	v_writelane_b32 v239, s69, 16
	v_writelane_b32 v239, s72, 17
	s_nop 1
	v_writelane_b32 v239, s73, 18
	v_writelane_b32 v239, s25, 19
	v_writelane_b32 v239, s24, 20
	s_mov_b32 s101, 0
	s_mov_b32 s100, 0
	s_branch .LBB0_11

.Lxb_census_done:
	s_add_u32 s10, s72, 0xfc00
	s_addc_u32 s11, s73, 0
	global_load_dword v4, v165, s[10:11] offset:0 sc1
	global_load_dword v5, v165, s[10:11] offset:256 sc1
	global_load_dword v6, v165, s[10:11] offset:512 sc1
	global_load_dword v7, v165, s[10:11] offset:768 sc1
	global_load_dword v8, v165, s[10:11] offset:1024 sc1
	global_load_dword v9, v165, s[10:11] offset:1280 sc1
	global_load_dword v10, v165, s[10:11] offset:1536 sc1
	global_load_dword v11, v165, s[10:11] offset:1792 sc1
	v_readlane_b32 s8, v240, 60
	v_max_u32_e32 v0, 1, v16
	s_max_u32 s9, s9, 1
	v_mov_b32_e32 v2, s8
	v_mov_b32_e32 v1, s9
	ds_write_b64 v2, v[0:1]
	s_waitcnt vmcnt(0)
	v_add_u32_e32 v12, -1, v4
	v_and_b32_e32 v4, v12, v4
	v_add_u32_e32 v12, -1, v5
	v_and_b32_e32 v5, v12, v5
	v_add_u32_e32 v12, -1, v6
	v_and_b32_e32 v6, v12, v6
	v_add_u32_e32 v12, -1, v7
	v_and_b32_e32 v7, v12, v7
	v_add_u32_e32 v12, -1, v8
	v_and_b32_e32 v8, v12, v8
	v_add_u32_e32 v12, -1, v9
	v_and_b32_e32 v9, v12, v9
	v_add_u32_e32 v12, -1, v10
	v_and_b32_e32 v10, v12, v10
	v_add_u32_e32 v12, -1, v11
	v_and_b32_e32 v11, v12, v11
	v_or3_b32 v4, v4, v5, v6
	v_or3_b32 v7, v7, v8, v9
	v_or3_b32 v10, v10, v11, v4
	v_or_b32_e32 v4, v10, v7
	v_xor_b32_e32 v5, 8, v1
	v_xor_b32_e32 v6, 32, v0
	v_or3_b32 v4, v4, v5, v6
	v_cmp_eq_u32_e32 vcc, 0, v4
	v_cndmask_b32_e64 v4, 2, 1, vcc
	ds_write_b32 v2, v4 offset:8
.Lxb_have:
	v_readfirstlane_b32 s10, v0
	v_readfirstlane_b32 s11, v1
	v_readlane_b32 s8, v240, 60
	s_add_u32 s12, s6, s3
	s_addc_u32 s13, s7, 0
	v_mov_b32_e32 v2, 1
	s_add_i32 s101, s101, 1
	s_mul_i32 s10, s10, s101
	v_mov_b32_e32 v4, s8
	ds_read_b32 v4, v4 offset:8
	global_atomic_add v3, v196, v2, s[12:13] offset:1024 sc0
	buffer_inv sc1
	v_readlane_b32 s8, v240, 0
	s_lshl_b32 s8, s8, 6
	s_add_u32 s8, s8, 0x4000
	s_add_u32 s14, s6, s8
	s_addc_u32 s15, s7, 0
	s_mov_b32 s9, 0
	s_waitcnt lgkmcnt(0)
	v_readfirstlane_b32 s8, v4
	s_cmp_eq_u32 s8, 1
	s_cbranch_scc0 .Lxb_grid
	s_mov_b32 s8, 0x1c78f1e0
	s_bitcmp1_b32 s8, s70
	s_cbranch_scc0 .Lxb_grid
	s_waitcnt vmcnt(1)
	v_add_u32_e32 v3, 1, v3
	v_cmp_gt_u32_e32 vcc, s10, v3
	s_cbranch_vccz .Lxb_done
.Lxb_lpoll:
	global_load_dword v3, v196, s[12:13] offset:1024 sc1
	s_add_i32 s9, s9, 1
	s_waitcnt vmcnt(0)
	v_cmp_gt_u32_e32 vcc, s10, v3
	s_cbranch_vccz .Lxb_done
	s_cmp_gt_u32 s9, 0x2000
	s_cbranch_scc1 .Lxb_done
	s_sleep 1
	s_branch .Lxb_lpoll
.Lxb_grid:
	s_add_i32 s100, s100, 1
	s_mul_i32 s11, s11, s100
	s_waitcnt vmcnt(1)
	v_add_u32_e32 v3, 1, v3
	v_cmp_eq_u32_e32 vcc, s10, v3
	s_cbranch_vccz .Lxb_poll
	buffer_wbl2 sc1
	v_readlane_b32 s12, v240, 46
	v_readlane_b32 s13, v240, 47
	s_waitcnt vmcnt(0)
	s_nop 3
	global_atomic_add v3, v165, v2, s[12:13] sc0
	s_waitcnt vmcnt(0)
	v_add_u32_e32 v3, 1, v3
	v_cmp_eq_u32_e32 vcc, s11, v3
	s_cbranch_vccz .Lxb_poll
	s_add_u32 s12, s6, 0x4000
	s_addc_u32 s13, s7, 0
	s_mov_b64 exec, -1
	v_mbcnt_lo_u32_b32 v3, -1, 0
	v_mbcnt_hi_u32_b32 v3, -1, v3
	v_mov_b32_e32 v2, 1
	v_lshlrev_b32_e32 v3, 6, v3
	v_add_u32_e32 v4, 0x1000, v3
	v_add_u32_e32 v5, 0x2000, v3
	v_add_u32_e32 v6, 0x3000, v3
	global_atomic_add v3, v2, s[12:13]
	global_atomic_add v4, v2, s[12:13]
	global_atomic_add v5, v2, s[12:13]
	global_atomic_add v6, v2, s[12:13]
	s_waitcnt vmcnt(4)
	s_mov_b64 exec, 1
	s_branch .LBB0_463
.Lxb_poll:
	global_load_dword v3, v165, s[14:15] sc1
	s_add_i32 s9, s9, 1
	s_waitcnt vmcnt(0)
	v_cmp_gt_u32_e32 vcc, s100, v3
	s_cbranch_vccz .Lxb_done
	s_cmp_gt_u32 s9, 0x40000
	s_cbranch_scc1 .Lxb_done
	s_sleep 1
	s_branch .Lxb_poll
